# MLA loop: waves 4-7 staggered half a trip behind waves 0-3 (per-half barrier position, 4-stage LDS ring)
# baseline (speedup 1.0000x reference)
.LBB0_251:
	s_or_b64 exec, exec, s[2:3]
	v_add_f32_e32 v100, 0, v114
	v_add_f32_e32 v80, 0, v80
	v_add_f32_e32 v100, v115, v100
	v_add_f32_e32 v80, v81, v80
	v_add_f32_e32 v100, v116, v100
	v_add_f32_e32 v80, v82, v80
	v_add_f32_e32 v100, v117, v100
	v_add_f32_e32 v80, v83, v80
	v_add_f32_e32 v100, v118, v100
	v_add_f32_e32 v80, v84, v80
	v_add_f32_e32 v100, v119, v100
	v_add_f32_e32 v80, v85, v80
	v_add_f32_e32 v100, v120, v100
	v_add_f32_e32 v80, v86, v80
	v_add_f32_e32 v100, v121, v100
	v_add_f32_e32 v80, v87, v80
	v_add_f32_e32 v100, v122, v100
	v_add_f32_e32 v80, v88, v80
	v_add_f32_e32 v100, v123, v100
	v_add_f32_e32 v80, v89, v80
	v_add_f32_e32 v100, v124, v100
	v_add_f32_e32 v80, v90, v80
	v_add_f32_e32 v100, v125, v100
	v_add_f32_e32 v80, v91, v80
	v_add_f32_e32 v100, v126, v100
	v_add_f32_e32 v80, v92, v80
	v_add_f32_e32 v100, v127, v100
	v_add_f32_e32 v80, v93, v80
	v_add_f32_e32 v100, v176, v100
	v_add_f32_e32 v80, v94, v80
	v_add_f32_e32 v100, v177, v100
	v_add_f32_e32 v80, v95, v80
	v_add_f32_e32 v100, v178, v100
	v_add_f32_e32 v64, v64, v80
	v_add_f32_e32 v100, v179, v100
	v_add_f32_e32 v64, v65, v64
	v_add_f32_e32 v100, v180, v100
	v_add_f32_e32 v64, v66, v64
	v_add_f32_e32 v100, v181, v100
	v_add_f32_e32 v64, v67, v64
	v_add_f32_e32 v100, v182, v100
	v_add_f32_e32 v64, v68, v64
	v_add_f32_e32 v100, v183, v100
	v_add_f32_e32 v64, v69, v64
	v_add_f32_e32 v100, v184, v100
	v_add_f32_e32 v64, v70, v64
	v_add_f32_e32 v100, v185, v100
	v_add_f32_e32 v64, v71, v64
	v_add_f32_e32 v100, v186, v100
	v_add_f32_e32 v64, v72, v64
	v_add_f32_e32 v100, v187, v100
	v_add_f32_e32 v64, v73, v64
	v_add_f32_e32 v100, v200, v100
	v_add_f32_e32 v64, v74, v64
	v_add_f32_e32 v100, v201, v100
	v_add_f32_e32 v64, v75, v64
	v_add_f32_e32 v100, v202, v100
	v_add_f32_e32 v64, v76, v64
	v_add_f32_e32 v100, v104, v100
	v_add_f32_e32 v64, v77, v64
	v_add_f32_e32 v100, v105, v100
	v_add_f32_e32 v64, v78, v64
	v_mul_u32_u24_e32 v220, 0xd0, v109
	v_mul_u32_u24_e32 v221, 0x90, v109
	v_add_f32_e32 v109, v106, v100
	v_add_f32_e32 v111, v79, v64
	v_pk_add_f32 v[202:203], v[108:109], 0 op_sel_hi:[1,0]
	v_pk_add_f32 v[200:201], v[110:111], 0 op_sel_hi:[1,0]
	v_add_u32_e32 v64, 0x8800, v113
	s_mov_b32 s9, 2
	s_waitcnt vmcnt(0)
	ds_write2_b64 v64, v[96:97], v[98:99] offset0:128 offset1:130
	s_movk_i32 s0, 0x6000
	v_lshl_add_u64 v[184:185], v[194:195], 0, s[0:1]
	v_lshl_add_u64 v[180:181], v[196:197], 0, s[0:1]
	s_movk_i32 s0, 0x100
	v_lshl_add_u64 v[176:177], v[198:199], 0, s[0:1]
	global_load_dwordx4 v[184:187], v[184:185], off
	global_load_dwordx4 v[180:183], v[180:181], off
	global_load_dwordx4 v[176:179], v[176:177], off
	s_movk_i32 s2, 0x5800
	v_add3_u32 v220, v220, v188, s2
	s_movk_i32 s2, 0x3400
	v_add3_u32 v221, v221, v188, s2
	v_add_u32_e32 v238, 0xe000, v219
	v_add_u32_e32 v219, 0x13800, v219
	v_xor_b32_e32 v64, 0x80000000, v202
	v_mov_b32_e32 v65, v64
	v_mov_b32_e32 v66, v64
	v_mov_b32_e32 v67, v64
	v_mov_b32_e32 v68, v64
	v_mov_b32_e32 v69, v64
	v_mov_b32_e32 v70, v64
	v_mov_b32_e32 v71, v64
	v_mov_b32_e32 v72, v64
	v_mov_b32_e32 v73, v64
	v_mov_b32_e32 v74, v64
	v_mov_b32_e32 v75, v64
	v_mov_b32_e32 v76, v64
	v_mov_b32_e32 v77, v64
	v_mov_b32_e32 v78, v64
	v_mov_b32_e32 v79, v64
	v_mov_b32_e32 v96, 0xff800000
	v_mov_b32_e32 v97, 0xff800000
	v_mov_b32_e32 v98, 0xff800000
	v_mov_b32_e32 v99, 0xff800000
	v_mov_b32_e32 v100, 0xff800000
	v_mov_b32_e32 v101, 0xff800000
	v_mov_b32_e32 v102, 0xff800000
	v_mov_b32_e32 v103, 0xff800000
	v_mov_b32_e32 v104, 0xff800000
	v_mov_b32_e32 v105, 0xff800000
	v_mov_b32_e32 v106, 0xff800000
	v_mov_b32_e32 v107, 0xff800000
	v_mov_b32_e32 v108, 0xff800000
	v_mov_b32_e32 v109, 0xff800000
	v_mov_b32_e32 v110, 0xff800000
	v_mov_b32_e32 v111, 0xff800000
	v_mov_b32_e32 v80, 0xff800000
	v_mov_b32_e32 v81, 0xff800000
	v_mov_b32_e32 v82, 0xff800000
	v_mov_b32_e32 v83, 0xff800000
	v_mov_b32_e32 v84, 0xff800000
	v_mov_b32_e32 v85, 0xff800000
	v_mov_b32_e32 v86, 0xff800000
	v_mov_b32_e32 v87, 0xff800000
	v_mov_b32_e32 v88, 0xff800000
	v_mov_b32_e32 v89, 0xff800000
	v_mov_b32_e32 v90, 0xff800000
	v_mov_b32_e32 v91, 0xff800000
	v_mov_b32_e32 v92, 0xff800000
	v_mov_b32_e32 v93, 0xff800000
	v_mov_b32_e32 v94, 0xff800000
	v_mov_b32_e32 v95, 0xff800000
	s_mov_b32 s10, 1
	s_waitcnt vmcnt(0)
	ds_write_b128 v216, v[184:187] offset:45056
	s_and_saveexec_b64 vcc, s[4:5]
	ds_write_b128 v217, v[180:183] offset:45056
	s_mov_b64 exec, vcc
	ds_write2_b64 v238, v[176:177], v[178:179] offset0:128 offset1:130
	s_nop 3
	v_add_u32_e32 v216, 0x10800, v216
	v_add_u32_e32 v217, 0x10800, v217
	s_mov_b32 s0, 0x9000
	v_lshl_add_u64 v[184:185], v[194:195], 0, s[0:1]
	v_lshl_add_u64 v[180:181], v[196:197], 0, s[0:1]
	s_movk_i32 s0, 0x180
	v_lshl_add_u64 v[176:177], v[198:199], 0, s[0:1]
	global_load_dwordx4 v[184:187], v[184:185], off
	global_load_dwordx4 v[180:183], v[180:181], off
	global_load_dwordx4 v[176:179], v[176:177], off
	v_readfirstlane_b32 s3, v204
	s_nop 3
	s_lshr_b32 s3, s3, 8
	s_min_u32 s3, s3, 1
	s_waitcnt lgkmcnt(0)
	s_barrier
	s_cmp_eq_u32 s3, 0
	s_cbranch_scc1 .Lmla_nbe
	s_setprio 1
	s_barrier
.Lmla_nbe:
	ds_read_b128 v[222:225], v220
	ds_read_b128 v[226:229], v220 offset:6656
	ds_read_b128 v[230:233], v220 offset:32
	ds_read_b128 v[234:237], v220 offset:6688
.Lmla_loop:
	s_waitcnt lgkmcnt(3)
	v_mfma_f32_32x32x16_bf16 v[112:127], v[222:225], v[128:131], v[64:79]
	ds_read_b128 v[222:225], v220 offset:64
	v_exp_f32_e32 v80, v80
	v_exp_f32_e32 v81, v81
	v_exp_f32_e32 v82, v82
	v_exp_f32_e32 v83, v83
	v_exp_f32_e32 v84, v84
	s_waitcnt lgkmcnt(3)
	v_mfma_f32_32x32x16_bf16 v[64:79], v[226:229], v[128:131], v[64:79]
	ds_read_b128 v[226:229], v220 offset:6720
	v_exp_f32_e32 v85, v85
	v_exp_f32_e32 v86, v86
	v_exp_f32_e32 v87, v87
	v_exp_f32_e32 v88, v88
	v_add_f32_e32 v201, v201, v80
	s_waitcnt lgkmcnt(3)
	v_mfma_f32_32x32x16_bf16 v[112:127], v[230:233], v[132:135], v[112:127]
	ds_read_b128 v[230:233], v220 offset:96
	v_exp_f32_e32 v89, v89
	v_add_f32_e32 v201, v201, v81
	v_exp_f32_e32 v90, v90
	v_add_f32_e32 v201, v201, v82
	v_exp_f32_e32 v91, v91
	v_add_f32_e32 v201, v201, v83
	s_waitcnt lgkmcnt(3)
	v_mfma_f32_32x32x16_bf16 v[64:79], v[234:237], v[132:135], v[64:79]
	ds_read_b128 v[234:237], v220 offset:6752
	v_exp_f32_e32 v92, v92
	v_add_f32_e32 v201, v201, v84
	v_exp_f32_e32 v93, v93
	v_add_f32_e32 v201, v201, v85
	v_exp_f32_e32 v94, v94
	v_add_f32_e32 v201, v201, v86
	s_waitcnt lgkmcnt(3)
	v_mfma_f32_32x32x16_bf16 v[112:127], v[222:225], v[136:139], v[112:127]
	ds_read_b128 v[222:225], v220 offset:128
	v_exp_f32_e32 v95, v95
	v_add_f32_e32 v201, v201, v87
	v_cvt_pk_bf16_f32 v80, v80, v81
	v_cvt_pk_bf16_f32 v81, v82, v83
	v_cvt_pk_bf16_f32 v82, v84, v85
	v_cvt_pk_bf16_f32 v83, v86, v87
	v_exp_f32_e32 v96, v96
	v_add_f32_e32 v201, v201, v88
	s_waitcnt lgkmcnt(3)
	v_mfma_f32_32x32x16_bf16 v[64:79], v[226:229], v[136:139], v[64:79]
	ds_read_b128 v[226:229], v220 offset:6784
	v_exp_f32_e32 v97, v97
	v_add_f32_e32 v201, v201, v89
	v_exp_f32_e32 v98, v98
	v_add_f32_e32 v201, v201, v90
	v_exp_f32_e32 v99, v99
	v_add_f32_e32 v201, v201, v91
	s_waitcnt lgkmcnt(3)
	v_mfma_f32_32x32x16_bf16 v[112:127], v[230:233], v[140:143], v[112:127]
	ds_read_b128 v[230:233], v220 offset:160
	v_exp_f32_e32 v100, v100
	v_add_f32_e32 v201, v201, v92
	v_exp_f32_e32 v101, v101
	v_add_f32_e32 v201, v201, v93
	v_exp_f32_e32 v102, v102
	v_add_f32_e32 v201, v201, v94
	s_waitcnt lgkmcnt(3)
	v_mfma_f32_32x32x16_bf16 v[64:79], v[234:237], v[140:143], v[64:79]
	ds_read_b128 v[234:237], v220 offset:6816
	v_exp_f32_e32 v103, v103
	v_add_f32_e32 v201, v201, v95
	v_cvt_pk_bf16_f32 v88, v88, v89
	v_cvt_pk_bf16_f32 v89, v90, v91
	v_cvt_pk_bf16_f32 v90, v92, v93
	v_cvt_pk_bf16_f32 v91, v94, v95
	v_exp_f32_e32 v104, v104
	v_add_f32_e32 v201, v201, v96
	s_waitcnt lgkmcnt(3)
	v_mfma_f32_32x32x16_bf16 v[112:127], v[222:225], v[144:147], v[112:127]
	ds_read_b128 v[222:225], v221 offset:64
	v_exp_f32_e32 v105, v105
	v_add_f32_e32 v201, v201, v97
	v_exp_f32_e32 v106, v106
	v_add_f32_e32 v201, v201, v98
	v_exp_f32_e32 v107, v107
	v_add_f32_e32 v201, v201, v99
	s_waitcnt lgkmcnt(3)
	v_mfma_f32_32x32x16_bf16 v[64:79], v[226:229], v[144:147], v[64:79]
	ds_read_b128 v[226:229], v221 offset:4672
	v_exp_f32_e32 v108, v108
	v_add_f32_e32 v201, v201, v100
	v_exp_f32_e32 v109, v109
	v_add_f32_e32 v201, v201, v101
	v_exp_f32_e32 v110, v110
	v_add_f32_e32 v201, v201, v102
	s_waitcnt lgkmcnt(3)
	v_mfma_f32_32x32x16_bf16 v[112:127], v[230:233], v[148:151], v[112:127]
	ds_read_b128 v[230:233], v221 offset:96
	v_exp_f32_e32 v111, v111
	v_add_f32_e32 v201, v201, v103
	v_cvt_pk_bf16_f32 v96, v96, v97
	v_cvt_pk_bf16_f32 v97, v98, v99
	v_cvt_pk_bf16_f32 v98, v100, v101
	v_cvt_pk_bf16_f32 v99, v102, v103
	v_add_f32_e32 v201, v201, v104
	v_add_f32_e32 v201, v201, v105
	v_add_f32_e32 v201, v201, v106
	s_waitcnt lgkmcnt(3)
	v_mfma_f32_32x32x16_bf16 v[64:79], v[234:237], v[148:151], v[64:79]
	ds_read_b128 v[234:237], v221 offset:4704
	v_add_f32_e32 v201, v201, v107
	v_add_f32_e32 v201, v201, v108
	v_add_f32_e32 v201, v201, v109
	v_add_f32_e32 v201, v201, v110
	v_add_f32_e32 v201, v201, v111
	v_cvt_pk_bf16_f32 v104, v104, v105
	v_cvt_pk_bf16_f32 v105, v106, v107
	v_cvt_pk_bf16_f32 v106, v108, v109
	v_cvt_pk_bf16_f32 v107, v110, v111
	s_waitcnt lgkmcnt(3)
	v_mfma_f32_32x32x16_bf16 v[0:15], v[222:225], v[80:83], v[0:15]
	ds_read_b128 v[222:225], v221
	s_waitcnt lgkmcnt(3)
	v_mfma_f32_32x32x16_bf16 v[16:31], v[226:229], v[80:83], v[16:31]
	ds_read_b128 v[226:229], v221 offset:4608
	s_waitcnt lgkmcnt(3)
	v_mfma_f32_32x32x16_bf16 v[0:15], v[230:233], v[88:91], v[0:15]
	ds_read_b128 v[230:233], v221 offset:32
	v_xor_b32_e32 v80, 0x80000000, v200
	v_mov_b32_e32 v81, v80
	v_mov_b32_e32 v82, v80
	v_mov_b32_e32 v83, v80
	v_mov_b32_e32 v84, v80
	v_mov_b32_e32 v85, v80
	v_mov_b32_e32 v86, v80
	v_mov_b32_e32 v87, v80
	v_mov_b32_e32 v92, v80
	v_mov_b32_e32 v93, v80
	s_waitcnt lgkmcnt(3)
	v_mfma_f32_32x32x16_bf16 v[16:31], v[234:237], v[88:91], v[16:31]
	ds_read_b128 v[234:237], v221 offset:4640
	v_mov_b32_e32 v94, v80
	v_mov_b32_e32 v95, v80
	v_max3_f32 v238, v112, v113, v114
	v_max3_f32 v238, v238, v115, v116
	v_max3_f32 v238, v238, v117, v118
	v_max3_f32 v238, v238, v119, v120
	v_max3_f32 v239, v64, v65, v66
	v_max3_f32 v238, v238, v121, v122
	v_max3_f32 v239, v239, v67, v68
	v_max3_f32 v238, v238, v123, v124
	s_waitcnt lgkmcnt(3)
	v_mfma_f32_32x32x16_bf16 v[0:15], v[222:225], v[96:99], v[0:15]
	ds_read_b128 v[222:225], v220
	v_mov_b32_e32 v88, v80
	v_mov_b32_e32 v89, v80
	v_mov_b32_e32 v90, v80
	v_mov_b32_e32 v91, v80
	v_max3_f32 v239, v239, v69, v70
	v_max3_f32 v238, v238, v125, v126
	v_max3_f32 v239, v239, v71, v72
	v_max_f32_e32 v238, v238, v127
	v_max3_f32 v239, v239, v73, v74
	v_max3_f32 v239, v239, v75, v76
	s_waitcnt lgkmcnt(3)
	v_mfma_f32_32x32x16_bf16 v[16:31], v[226:229], v[96:99], v[16:31]
	ds_read_b128 v[226:229], v220 offset:6656
	s_mov_b32 s2, 0x5800
	s_cmp_eq_u32 s10, 0
	s_cselect_b32 s2, 0xfffef800, s2
	v_add_u32_e32 v221, s2, v221
	v_max3_f32 v239, v239, v77, v78
	v_max_f32_e32 v239, v239, v79
	v_max_f32_e32 v238, v238, v239
	ds_bpermute_b32 v188, v218, v238
	s_waitcnt lgkmcnt(4)
	v_mfma_f32_32x32x16_bf16 v[0:15], v[230:233], v[104:107], v[0:15]
	ds_read_b128 v[230:233], v220 offset:32
	s_waitcnt lgkmcnt(4)
	v_mfma_f32_32x32x16_bf16 v[16:31], v[234:237], v[104:107], v[16:31]
	ds_read_b128 v[234:237], v220 offset:6688
	s_cmp_eq_u32 s3, 0
	s_cbranch_scc0 .Lmla_nb0
	s_barrier
.Lmla_nb0:
	s_waitcnt lgkmcnt(2)
	v_max_f32_e32 v238, v238, v188
	v_cmp_lt_f32_e32 vcc, 0x41000000, v238
	s_cbranch_vccz .Lmla_skipA
	s_nop 15
	v_max_f32_e32 v238, 0, v238
	v_exp_f32_e64 v239, -v238
	v_add_f32_e32 v202, v202, v238
	s_nop 0
	v_mul_f32_e32 v203, v203, v239
	v_mul_f32_e32 v32, v32, v239
	v_mul_f32_e32 v33, v33, v239
	v_mul_f32_e32 v34, v34, v239
	v_mul_f32_e32 v35, v35, v239
	v_mul_f32_e32 v36, v36, v239
	v_mul_f32_e32 v37, v37, v239
	v_mul_f32_e32 v38, v38, v239
	v_mul_f32_e32 v39, v39, v239
	v_mul_f32_e32 v40, v40, v239
	v_mul_f32_e32 v41, v41, v239
	v_mul_f32_e32 v42, v42, v239
	v_mul_f32_e32 v43, v43, v239
	v_mul_f32_e32 v44, v44, v239
	v_mul_f32_e32 v45, v45, v239
	v_mul_f32_e32 v46, v46, v239
	v_mul_f32_e32 v47, v47, v239
	v_mul_f32_e32 v48, v48, v239
	v_mul_f32_e32 v49, v49, v239
	v_mul_f32_e32 v50, v50, v239
	v_mul_f32_e32 v51, v51, v239
	v_mul_f32_e32 v52, v52, v239
	v_mul_f32_e32 v53, v53, v239
	v_mul_f32_e32 v54, v54, v239
	v_mul_f32_e32 v55, v55, v239
	v_mul_f32_e32 v56, v56, v239
	v_mul_f32_e32 v57, v57, v239
	v_mul_f32_e32 v58, v58, v239
	v_mul_f32_e32 v59, v59, v239
	v_mul_f32_e32 v60, v60, v239
	v_mul_f32_e32 v61, v61, v239
	v_mul_f32_e32 v62, v62, v239
	v_mul_f32_e32 v63, v63, v239
	v_sub_f32_e32 v112, v112, v238
	v_sub_f32_e32 v113, v113, v238
	v_sub_f32_e32 v114, v114, v238
	v_sub_f32_e32 v115, v115, v238
	v_sub_f32_e32 v116, v116, v238
	v_sub_f32_e32 v117, v117, v238
	v_sub_f32_e32 v118, v118, v238
	v_sub_f32_e32 v119, v119, v238
	v_sub_f32_e32 v120, v120, v238
	v_sub_f32_e32 v121, v121, v238
	v_sub_f32_e32 v122, v122, v238
	v_sub_f32_e32 v123, v123, v238
	v_sub_f32_e32 v124, v124, v238
	v_sub_f32_e32 v125, v125, v238
	v_sub_f32_e32 v126, v126, v238
	v_sub_f32_e32 v127, v127, v238
	v_sub_f32_e32 v64, v64, v238
	v_sub_f32_e32 v65, v65, v238
	v_sub_f32_e32 v66, v66, v238
	v_sub_f32_e32 v67, v67, v238
	v_sub_f32_e32 v68, v68, v238
	v_sub_f32_e32 v69, v69, v238
	v_sub_f32_e32 v70, v70, v238
	v_sub_f32_e32 v71, v71, v238
	v_sub_f32_e32 v72, v72, v238
	v_sub_f32_e32 v73, v73, v238
	v_sub_f32_e32 v74, v74, v238
	v_sub_f32_e32 v75, v75, v238
	v_sub_f32_e32 v76, v76, v238
	v_sub_f32_e32 v77, v77, v238
	v_sub_f32_e32 v78, v78, v238
	v_sub_f32_e32 v79, v79, v238
.Lmla_skipA:
	v_mfma_f32_32x32x16_bf16 v[96:111], v[222:225], v[152:155], v[80:95]
	ds_read_b128 v[222:225], v220 offset:64
	s_waitcnt vmcnt(0)
	ds_write_b128 v216, v[184:187]
	s_and_saveexec_b64 vcc, s[4:5]
	ds_write_b128 v217, v[180:183]
	s_mov_b64 exec, vcc
	ds_write2_b64 v219, v[176:177], v[178:179] offset0:128 offset1:130
	v_exp_f32_e32 v64, v64
	v_exp_f32_e32 v65, v65
	v_exp_f32_e32 v66, v66
	v_mfma_f32_32x32x16_bf16 v[80:95], v[226:229], v[152:155], v[80:95]
	ds_read_b128 v[226:229], v220 offset:6720
	v_exp_f32_e32 v67, v67
	v_exp_f32_e32 v68, v68
	v_exp_f32_e32 v69, v69
	v_exp_f32_e32 v70, v70
	v_exp_f32_e32 v71, v71
	s_waitcnt lgkmcnt(6)
	v_mfma_f32_32x32x16_bf16 v[96:111], v[230:233], v[156:159], v[96:111]
	ds_read_b128 v[230:233], v220 offset:96
	s_add_i32 s2, s9, 2
	s_min_u32 s2, s2, 0x7f
	s_mul_i32 s0, s2, 0x3000
	v_lshl_add_u64 v[184:185], v[194:195], 0, s[0:1]
	v_lshl_add_u64 v[180:181], v[196:197], 0, s[0:1]
	s_lshl_b32 s0, s2, 7
	v_lshl_add_u64 v[176:177], v[198:199], 0, s[0:1]
	global_load_dwordx4 v[184:187], v[184:185], off
	global_load_dwordx4 v[180:183], v[180:181], off
	global_load_dwordx4 v[176:179], v[176:177], off
	v_exp_f32_e32 v72, v72
	v_add_f32_e32 v203, v203, v64
	s_waitcnt lgkmcnt(6)
	v_mfma_f32_32x32x16_bf16 v[80:95], v[234:237], v[156:159], v[80:95]
	ds_read_b128 v[234:237], v220 offset:6752
	s_mov_b32 s2, 0x5800
	s_cmp_eq_u32 s10, 1
	s_cselect_b32 s2, 0xfffef800, s2
	v_add_u32_e32 v216, s2, v216
	v_add_u32_e32 v217, s2, v217
	v_add_u32_e32 v219, s2, v219
	v_exp_f32_e32 v73, v73
	v_add_f32_e32 v203, v203, v65
	v_exp_f32_e32 v74, v74
	v_add_f32_e32 v203, v203, v66
	s_waitcnt lgkmcnt(6)
	v_mfma_f32_32x32x16_bf16 v[96:111], v[222:225], v[160:163], v[96:111]
	ds_read_b128 v[222:225], v220 offset:128
	v_exp_f32_e32 v75, v75
	v_add_f32_e32 v203, v203, v67
	v_exp_f32_e32 v76, v76
	v_add_f32_e32 v203, v203, v68
	v_exp_f32_e32 v77, v77
	v_add_f32_e32 v203, v203, v69
	s_waitcnt lgkmcnt(3)
	v_mfma_f32_32x32x16_bf16 v[80:95], v[226:229], v[160:163], v[80:95]
	ds_read_b128 v[226:229], v220 offset:6784
	v_exp_f32_e32 v78, v78
	v_add_f32_e32 v203, v203, v70
	v_exp_f32_e32 v79, v79
	v_add_f32_e32 v203, v203, v71
	v_cvt_pk_bf16_f32 v64, v64, v65
	v_cvt_pk_bf16_f32 v65, v66, v67
	v_cvt_pk_bf16_f32 v66, v68, v69
	v_cvt_pk_bf16_f32 v67, v70, v71
	s_waitcnt lgkmcnt(3)
	v_mfma_f32_32x32x16_bf16 v[96:111], v[230:233], v[164:167], v[96:111]
	ds_read_b128 v[230:233], v220 offset:160
	v_exp_f32_e32 v112, v112
	v_add_f32_e32 v203, v203, v72
	v_exp_f32_e32 v113, v113
	v_add_f32_e32 v203, v203, v73
	v_exp_f32_e32 v114, v114
	v_add_f32_e32 v203, v203, v74
	s_waitcnt lgkmcnt(3)
	v_mfma_f32_32x32x16_bf16 v[80:95], v[234:237], v[164:167], v[80:95]
	ds_read_b128 v[234:237], v220 offset:6816
	v_exp_f32_e32 v115, v115
	v_add_f32_e32 v203, v203, v75
	v_exp_f32_e32 v116, v116
	v_add_f32_e32 v203, v203, v76
	v_exp_f32_e32 v117, v117
	v_add_f32_e32 v203, v203, v77
	s_waitcnt lgkmcnt(3)
	v_mfma_f32_32x32x16_bf16 v[96:111], v[222:225], v[168:171], v[96:111]
	ds_read_b128 v[222:225], v221 offset:64
	v_exp_f32_e32 v118, v118
	v_add_f32_e32 v203, v203, v78
	v_exp_f32_e32 v119, v119
	v_add_f32_e32 v203, v203, v79
	v_cvt_pk_bf16_f32 v72, v72, v73
	v_cvt_pk_bf16_f32 v73, v74, v75
	v_cvt_pk_bf16_f32 v74, v76, v77
	v_cvt_pk_bf16_f32 v75, v78, v79
	s_waitcnt lgkmcnt(3)
	v_mfma_f32_32x32x16_bf16 v[80:95], v[226:229], v[168:171], v[80:95]
	ds_read_b128 v[226:229], v221 offset:4672
	s_mov_b32 s2, 0x5800
	s_cmp_eq_u32 s10, 3
	s_cselect_b32 s2, 0xfffef800, s2
	v_add_u32_e32 v220, s2, v220
	v_exp_f32_e32 v120, v120
	v_add_f32_e32 v203, v203, v112
	v_exp_f32_e32 v121, v121
	v_add_f32_e32 v203, v203, v113
	v_exp_f32_e32 v122, v122
	v_add_f32_e32 v203, v203, v114
	s_waitcnt lgkmcnt(3)
	v_mfma_f32_32x32x16_bf16 v[96:111], v[230:233], v[172:175], v[96:111]
	ds_read_b128 v[230:233], v221 offset:96
	v_exp_f32_e32 v123, v123
	v_add_f32_e32 v203, v203, v115
	v_exp_f32_e32 v124, v124
	v_add_f32_e32 v203, v203, v116
	v_exp_f32_e32 v125, v125
	v_add_f32_e32 v203, v203, v117
	s_waitcnt lgkmcnt(3)
	v_mfma_f32_32x32x16_bf16 v[80:95], v[234:237], v[172:175], v[80:95]
	ds_read_b128 v[234:237], v221 offset:4704
	v_exp_f32_e32 v126, v126
	v_add_f32_e32 v203, v203, v118
	v_exp_f32_e32 v127, v127
	v_add_f32_e32 v203, v203, v119
	v_cvt_pk_bf16_f32 v112, v112, v113
	v_cvt_pk_bf16_f32 v113, v114, v115
	v_cvt_pk_bf16_f32 v114, v116, v117
	v_cvt_pk_bf16_f32 v115, v118, v119
	s_waitcnt lgkmcnt(3)
	v_mfma_f32_32x32x16_bf16 v[32:47], v[222:225], v[64:67], v[32:47]
	ds_read_b128 v[222:225], v221
	v_add_f32_e32 v203, v203, v120
	v_add_f32_e32 v203, v203, v121
	v_add_f32_e32 v203, v203, v122
	v_add_f32_e32 v203, v203, v123
	v_add_f32_e32 v203, v203, v124
	v_add_f32_e32 v203, v203, v125
	v_add_f32_e32 v203, v203, v126
	v_add_f32_e32 v203, v203, v127
	v_cvt_pk_bf16_f32 v120, v120, v121
	v_cvt_pk_bf16_f32 v121, v122, v123
	s_waitcnt lgkmcnt(3)
	v_mfma_f32_32x32x16_bf16 v[48:63], v[226:229], v[64:67], v[48:63]
	ds_read_b128 v[226:229], v221 offset:4608
	v_cvt_pk_bf16_f32 v122, v124, v125
	v_cvt_pk_bf16_f32 v123, v126, v127
	s_waitcnt lgkmcnt(3)
	v_mfma_f32_32x32x16_bf16 v[32:47], v[230:233], v[72:75], v[32:47]
	ds_read_b128 v[230:233], v221 offset:32
	v_max3_f32 v238, v96, v97, v98
	v_max3_f32 v238, v238, v99, v100
	v_max3_f32 v238, v238, v101, v102
	v_max3_f32 v238, v238, v103, v104
	s_waitcnt lgkmcnt(3)
	v_mfma_f32_32x32x16_bf16 v[48:63], v[234:237], v[72:75], v[48:63]
	ds_read_b128 v[234:237], v221 offset:4640
	v_max3_f32 v239, v80, v81, v82
	v_max3_f32 v238, v238, v105, v106
	v_max3_f32 v239, v239, v83, v84
	v_max3_f32 v238, v238, v107, v108
	v_max3_f32 v239, v239, v85, v86
	v_max3_f32 v238, v238, v109, v110
	v_max3_f32 v239, v239, v87, v88
	v_max_f32_e32 v238, v238, v111
	v_max3_f32 v239, v239, v89, v90
	v_max3_f32 v239, v239, v91, v92
	s_waitcnt lgkmcnt(3)
	v_mfma_f32_32x32x16_bf16 v[32:47], v[222:225], v[112:115], v[32:47]
	ds_read_b128 v[222:225], v220
	v_max3_f32 v239, v239, v93, v94
	v_max_f32_e32 v239, v239, v95
	v_max_f32_e32 v238, v238, v239
	ds_bpermute_b32 v188, v218, v238
	v_xor_b32_e32 v64, 0x80000000, v202
	v_mov_b32_e32 v65, v64
	v_mov_b32_e32 v66, v64
	v_mov_b32_e32 v67, v64
	v_mov_b32_e32 v68, v64
	v_mov_b32_e32 v69, v64
	v_mov_b32_e32 v70, v64
	s_waitcnt lgkmcnt(4)
	v_mfma_f32_32x32x16_bf16 v[48:63], v[226:229], v[112:115], v[48:63]
	ds_read_b128 v[226:229], v220 offset:6656
	v_mov_b32_e32 v71, v64
	v_mov_b32_e32 v72, v64
	v_mov_b32_e32 v73, v64
	v_mov_b32_e32 v74, v64
	v_mov_b32_e32 v75, v64
	v_mov_b32_e32 v76, v64
	v_mov_b32_e32 v77, v64
	v_mov_b32_e32 v78, v64
	v_mov_b32_e32 v79, v64
	s_waitcnt lgkmcnt(4)
	v_mfma_f32_32x32x16_bf16 v[32:47], v[230:233], v[120:123], v[32:47]
	ds_read_b128 v[230:233], v220 offset:32
	s_waitcnt lgkmcnt(2)
	v_max_f32_e32 v238, v238, v188
	v_cmp_lt_f32_e32 vcc, 0x41000000, v238
	s_cbranch_vccz .Lmla_skipB
	s_nop 15
	v_max_f32_e32 v238, 0, v238
	v_exp_f32_e64 v239, -v238
	v_add_f32_e32 v200, v200, v238
	s_nop 0
	v_mul_f32_e32 v201, v201, v239
	v_mul_f32_e32 v0, v0, v239
	v_mul_f32_e32 v1, v1, v239
	v_mul_f32_e32 v2, v2, v239
	v_mul_f32_e32 v3, v3, v239
	v_mul_f32_e32 v4, v4, v239
	v_mul_f32_e32 v5, v5, v239
	v_mul_f32_e32 v6, v6, v239
	v_mul_f32_e32 v7, v7, v239
	v_mul_f32_e32 v8, v8, v239
	v_mul_f32_e32 v9, v9, v239
	v_mul_f32_e32 v10, v10, v239
	v_mul_f32_e32 v11, v11, v239
	v_mul_f32_e32 v12, v12, v239
	v_mul_f32_e32 v13, v13, v239
	v_mul_f32_e32 v14, v14, v239
	v_mul_f32_e32 v15, v15, v239
	v_mul_f32_e32 v16, v16, v239
	v_mul_f32_e32 v17, v17, v239
	v_mul_f32_e32 v18, v18, v239
	v_mul_f32_e32 v19, v19, v239
	v_mul_f32_e32 v20, v20, v239
	v_mul_f32_e32 v21, v21, v239
	v_mul_f32_e32 v22, v22, v239
	v_mul_f32_e32 v23, v23, v239
	v_mul_f32_e32 v24, v24, v239
	v_mul_f32_e32 v25, v25, v239
	v_mul_f32_e32 v26, v26, v239
	v_mul_f32_e32 v27, v27, v239
	v_mul_f32_e32 v28, v28, v239
	v_mul_f32_e32 v29, v29, v239
	v_mul_f32_e32 v30, v30, v239
	v_mul_f32_e32 v31, v31, v239
	v_sub_f32_e32 v96, v96, v238
	v_sub_f32_e32 v97, v97, v238
	v_sub_f32_e32 v98, v98, v238
	v_sub_f32_e32 v99, v99, v238
	v_sub_f32_e32 v100, v100, v238
	v_sub_f32_e32 v101, v101, v238
	v_sub_f32_e32 v102, v102, v238
	v_sub_f32_e32 v103, v103, v238
	v_sub_f32_e32 v104, v104, v238
	v_sub_f32_e32 v105, v105, v238
	v_sub_f32_e32 v106, v106, v238
	v_sub_f32_e32 v107, v107, v238
	v_sub_f32_e32 v108, v108, v238
	v_sub_f32_e32 v109, v109, v238
	v_sub_f32_e32 v110, v110, v238
	v_sub_f32_e32 v111, v111, v238
	v_sub_f32_e32 v80, v80, v238
	v_sub_f32_e32 v81, v81, v238
	v_sub_f32_e32 v82, v82, v238
	v_sub_f32_e32 v83, v83, v238
	v_sub_f32_e32 v84, v84, v238
	v_sub_f32_e32 v85, v85, v238
	v_sub_f32_e32 v86, v86, v238
	v_sub_f32_e32 v87, v87, v238
	v_sub_f32_e32 v88, v88, v238
	v_sub_f32_e32 v89, v89, v238
	v_sub_f32_e32 v90, v90, v238
	v_sub_f32_e32 v91, v91, v238
	v_sub_f32_e32 v92, v92, v238
	v_sub_f32_e32 v93, v93, v238
	v_sub_f32_e32 v94, v94, v238
	v_sub_f32_e32 v95, v95, v238
.Lmla_skipB:
	v_mfma_f32_32x32x16_bf16 v[48:63], v[234:237], v[120:123], v[48:63]
	ds_read_b128 v[234:237], v220 offset:6688
	s_cmp_eq_u32 s3, 0
	s_cbranch_scc1 .Lmla_nb1
	s_barrier
.Lmla_nb1:
	s_add_i32 s10, s10, 1
	s_cmp_eq_u32 s10, 4
	s_cselect_b32 s10, 0, s10
	s_add_i32 s9, s9, 1
	s_cmpk_lg_i32 s9, 0x81
	s_cbranch_scc1 .Lmla_loop
	s_cmp_eq_u32 s3, 0
	s_cbranch_scc0 .Lmla_nbx
	s_barrier
.Lmla_nbx:
	s_waitcnt lgkmcnt(0)
	v_exp_f32_e32 v80, v80
	v_exp_f32_e32 v81, v81
	v_exp_f32_e32 v82, v82
	v_exp_f32_e32 v83, v83
	v_exp_f32_e32 v84, v84
	v_exp_f32_e32 v85, v85
	v_exp_f32_e32 v86, v86
	v_exp_f32_e32 v87, v87
	v_exp_f32_e32 v88, v88
	v_add_f32_e32 v201, v201, v80
	v_exp_f32_e32 v89, v89
	v_add_f32_e32 v201, v201, v81
	v_exp_f32_e32 v90, v90
	v_add_f32_e32 v201, v201, v82
	v_exp_f32_e32 v91, v91
	v_add_f32_e32 v201, v201, v83
	v_exp_f32_e32 v92, v92
	v_add_f32_e32 v201, v201, v84
	v_exp_f32_e32 v93, v93
	v_add_f32_e32 v201, v201, v85
	v_exp_f32_e32 v94, v94
	v_add_f32_e32 v201, v201, v86
	v_exp_f32_e32 v95, v95
	v_add_f32_e32 v201, v201, v87
	v_cvt_pk_bf16_f32 v80, v80, v81
	v_cvt_pk_bf16_f32 v81, v82, v83
	v_cvt_pk_bf16_f32 v82, v84, v85
	v_cvt_pk_bf16_f32 v83, v86, v87
	v_exp_f32_e32 v96, v96
	v_add_f32_e32 v201, v201, v88
	v_exp_f32_e32 v97, v97
	v_add_f32_e32 v201, v201, v89
	v_exp_f32_e32 v98, v98
	v_add_f32_e32 v201, v201, v90
	v_exp_f32_e32 v99, v99
	v_add_f32_e32 v201, v201, v91
	v_exp_f32_e32 v100, v100
	v_add_f32_e32 v201, v201, v92
	v_exp_f32_e32 v101, v101
	v_add_f32_e32 v201, v201, v93
	v_exp_f32_e32 v102, v102
	v_add_f32_e32 v201, v201, v94
	v_exp_f32_e32 v103, v103
	v_add_f32_e32 v201, v201, v95
	v_cvt_pk_bf16_f32 v88, v88, v89
	v_cvt_pk_bf16_f32 v89, v90, v91
	v_cvt_pk_bf16_f32 v90, v92, v93
	v_cvt_pk_bf16_f32 v91, v94, v95
	v_exp_f32_e32 v104, v104
	v_add_f32_e32 v201, v201, v96
	v_exp_f32_e32 v105, v105
	v_add_f32_e32 v201, v201, v97
	v_exp_f32_e32 v106, v106
	v_add_f32_e32 v201, v201, v98
	v_exp_f32_e32 v107, v107
	v_add_f32_e32 v201, v201, v99
	v_exp_f32_e32 v108, v108
	v_add_f32_e32 v201, v201, v100
	v_exp_f32_e32 v109, v109
	v_add_f32_e32 v201, v201, v101
	v_exp_f32_e32 v110, v110
	v_add_f32_e32 v201, v201, v102
	v_exp_f32_e32 v111, v111
	v_add_f32_e32 v201, v201, v103
	v_cvt_pk_bf16_f32 v96, v96, v97
	v_cvt_pk_bf16_f32 v97, v98, v99
	v_cvt_pk_bf16_f32 v98, v100, v101
	v_cvt_pk_bf16_f32 v99, v102, v103
	v_add_f32_e32 v201, v201, v104
	v_add_f32_e32 v201, v201, v105
	v_add_f32_e32 v201, v201, v106
	v_add_f32_e32 v201, v201, v107
	v_add_f32_e32 v201, v201, v108
	v_add_f32_e32 v201, v201, v109
	v_add_f32_e32 v201, v201, v110
	v_add_f32_e32 v201, v201, v111
	v_cvt_pk_bf16_f32 v104, v104, v105
	v_cvt_pk_bf16_f32 v105, v106, v107
	v_cvt_pk_bf16_f32 v106, v108, v109
	v_cvt_pk_bf16_f32 v107, v110, v111
	ds_read_b128 v[222:225], v221 offset:64
	ds_read_b128 v[226:229], v221 offset:4672
	ds_read_b128 v[230:233], v221 offset:96
	ds_read_b128 v[234:237], v221 offset:4704
	s_waitcnt lgkmcnt(3)
	v_mfma_f32_32x32x16_bf16 v[0:15], v[222:225], v[80:83], v[0:15]
	ds_read_b128 v[222:225], v221
	s_waitcnt lgkmcnt(3)
	v_mfma_f32_32x32x16_bf16 v[16:31], v[226:229], v[80:83], v[16:31]
	ds_read_b128 v[226:229], v221 offset:4608
	s_waitcnt lgkmcnt(3)
	v_mfma_f32_32x32x16_bf16 v[0:15], v[230:233], v[88:91], v[0:15]
	ds_read_b128 v[230:233], v221 offset:32
	s_waitcnt lgkmcnt(3)
	v_mfma_f32_32x32x16_bf16 v[16:31], v[234:237], v[88:91], v[16:31]
	ds_read_b128 v[234:237], v221 offset:4640
	s_waitcnt lgkmcnt(3)
	v_mfma_f32_32x32x16_bf16 v[0:15], v[222:225], v[96:99], v[0:15]
	s_waitcnt lgkmcnt(2)
	v_mfma_f32_32x32x16_bf16 v[16:31], v[226:229], v[96:99], v[16:31]
	s_waitcnt lgkmcnt(1)
	v_mfma_f32_32x32x16_bf16 v[0:15], v[230:233], v[104:107], v[0:15]
	s_waitcnt lgkmcnt(0)
	v_mfma_f32_32x32x16_bf16 v[16:31], v[234:237], v[104:107], v[16:31]
	s_setprio 0
	s_mov_b32 s3, 0
	s_barrier
	s_branch .LBB0_216
